# SWA_QKV epilogue: bias quads loaded once per tile (per-group load+vmcnt(0) round trips removed; s_nop 1 guards the dwordx4 store data)
# baseline (speedup 1.0000x reference)
; __device__ __forceinline__ u32x4 pack8(f32x4 a, f32x4 b) { u32x4 w; w.x = cvt_pk_bf16(a[0], a[1]); w.y = cvt_pk_bf16(a[2], a[3]); w.z = cvt_pk_bf16(b[0], b[1]); w.w = cvt_pk_bf16(b[2], b[3]); return w; }
; #define EPI_END } asm volatile("" ::: "memory"); }
;     __device__ __forceinline__ void operator()(const f32x4 (&acc)[2][2][4][2], const pg8::Unit& u, int wr, int wc, int fr, int fq) const {
;     ...
;             EPI_BEGIN { v0 += *(const f32x4*)(bias + col); v1 += *(const f32x4*)(bias + col + 4);
;                 if (col < 2048) { *(u32x4*)(o0 + (size_t)row * 2048 + col) = pack8(v0 * qs, v1 * qs); }
;                 else if (col < 2304) { *(u32x4*)(o1 + (size_t)row * 256 + (col - 2048)) = pack8(v0, v1); }
;                 else { const int d = col - 2304, b = row >> 13, t = row & 8191; bf16_t* vp = o2 + ((size_t)(b * 256 + d)) * 8192 + t; const u32x4 w = pack8(v0, v1);
;                     vp[0] = (bf16_t)(w.x & 0xffff); vp[8192] = (bf16_t)(w.x >> 16); vp[2 * 8192] = (bf16_t)(w.y & 0xffff); vp[3 * 8192] = (bf16_t)(w.y >> 16);
;                     vp[4 * 8192] = (bf16_t)(w.z & 0xffff); vp[5 * 8192] = (bf16_t)(w.z >> 16); vp[6 * 8192] = (bf16_t)(w.w & 0xffff); vp[7 * 8192] = (bf16_t)(w.w >> 16); } } EPI_END
.LBB0_880:
	s_andn2_b64 vcc, exec, s[18:19]
	s_cbranch_vccnz .LBB0_1048
	s_cmp_gt_i32 s52, 4
	s_mov_b64 s[18:19], -1
	s_cbranch_scc0 .LBB0_995
	v_readlane_b32 s18, v255, 34
	v_ashrrev_i32_e32 v157, 31, v156
	v_readlane_b32 s19, v255, 35
	v_ashrrev_i32_e32 v159, 31, v158
	v_and_b32_e32 v164, 0x1fcf, v158
	v_lshl_add_u64 v[134:135], v[156:157], 2, s[18:19]
	s_waitcnt lgkmcnt(0)
	global_load_dwordx4 v[190:193], v[134:135], off
	global_load_dwordx4 v[194:197], v[134:135], off offset:16
	global_load_dwordx4 v[198:201], v[134:135], off offset:512
	global_load_dwordx4 v[202:205], v[134:135], off offset:528
	s_ashr_i32 s18, s29, 5
	s_and_b32 s22, s18, 0xffffff00
	v_lshlrev_b64 v[136:137], 9, v[158:159]
	s_addk_i32 s22, 0xf700
	v_cmp_lt_i32_e64 s[44:45], s97, v156
	s_waitcnt vmcnt(0)
	s_nop 1
	v_mov_b32_e32 v128, v190
	v_mov_b32_e32 v129, v191
	v_mov_b32_e32 v130, v192
	v_mov_b32_e32 v131, v193
	v_mov_b32_e32 v166, v194
	v_mov_b32_e32 v167, v195
	v_mov_b32_e32 v168, v196
	v_mov_b32_e32 v169, v197
	v_pk_add_f32 v[162:163], v[126:127], v[130:131]
	v_pk_add_f32 v[128:129], v[124:125], v[128:129]
	v_pk_add_f32 v[160:161], v[122:123], v[168:169]
	v_pk_add_f32 v[130:131], v[120:121], v[166:167]
	s_and_saveexec_b64 s[18:19], s[44:45]
	s_xor_b64 s[18:19], exec, s[18:19]
	s_cbranch_execz .LBB0_887
	s_cmpk_gt_u32 s41, 0x8ff
	s_mov_b64 s[20:21], -1
	s_cbranch_scc0 .LBB0_885
	v_add_u32_e32 v132, s22, v156
	v_ashrrev_i32_e32 v133, 31, v132
	v_lshlrev_b64 v[132:133], 14, v[132:133]
	v_lshl_add_u64 v[132:133], s[70:71], 0, v[132:133]
	v_lshlrev_b32_e32 v180, 1, v164
	v_lshl_add_u64 v[132:133], v[132:133], 0, v[180:181]
	v_add_co_u32_e32 v166, vcc, s1, v132
	v_cvt_pk_bf16_f32 v155, v128, v129
	v_cvt_pk_bf16_f32 v165, v162, v163
	v_cvt_pk_bf16_f32 v168, v130, v131
	v_cvt_pk_bf16_f32 v169, v160, v161
	s_nop 1
	v_addc_co_u32_e32 v167, vcc, 0, v133, vcc
	global_store_short_d16_hi v[166:167], v155, off
	v_add_co_u32_e32 v166, vcc, s96, v132
	s_mov_b32 s20, 0xc000
	s_nop 0
	v_addc_co_u32_e32 v167, vcc, 0, v133, vcc
	global_store_short v[166:167], v165, off
	v_add_co_u32_e32 v166, vcc, s20, v132
	s_mov_b32 s20, 0x10000
	s_nop 0
	v_addc_co_u32_e32 v167, vcc, 0, v133, vcc
	global_store_short_d16_hi v[166:167], v165, off
	v_add_co_u32_e32 v166, vcc, s20, v132
	global_store_short v[132:133], v155, off
	s_nop 0
	v_addc_co_u32_e32 v167, vcc, 0, v133, vcc
	global_store_short v[166:167], v168, off
	v_add_co_u32_e32 v166, vcc, 0x14000, v132
	s_mov_b64 s[20:21], 0
	s_nop 0
	v_addc_co_u32_e32 v167, vcc, 0, v133, vcc
	global_store_short_d16_hi v[166:167], v168, off
	v_add_co_u32_e32 v166, vcc, 0x18000, v132
	s_nop 1
	v_addc_co_u32_e32 v167, vcc, 0, v133, vcc
	v_add_co_u32_e32 v132, vcc, 0x1c000, v132
	global_store_short v[166:167], v169, off
	s_nop 0
	v_addc_co_u32_e32 v133, vcc, 0, v133, vcc
	global_store_short_d16_hi v[132:133], v169, off

; __device__ __forceinline__ u32x4 pack8(f32x4 a, f32x4 b) { u32x4 w; w.x = cvt_pk_bf16(a[0], a[1]); w.y = cvt_pk_bf16(a[2], a[3]); w.z = cvt_pk_bf16(b[0], b[1]); w.w = cvt_pk_bf16(b[2], b[3]); return w; }
; #define EPI_END } asm volatile("" ::: "memory"); }
;     __device__ __forceinline__ void operator()(const f32x4 (&acc)[2][2][4][2], const pg8::Unit& u, int wr, int wc, int fr, int fq) const {
;     ...
;             EPI_BEGIN { v0 += *(const f32x4*)(bias + col); v1 += *(const f32x4*)(bias + col + 4);
;                 if (col < 2048) { *(u32x4*)(o0 + (size_t)row * 2048 + col) = pack8(v0 * qs, v1 * qs); }
;                 else if (col < 2304) { *(u32x4*)(o1 + (size_t)row * 256 + (col - 2048)) = pack8(v0, v1); }
;                 else { const int d = col - 2304, b = row >> 13, t = row & 8191; bf16_t* vp = o2 + ((size_t)(b * 256 + d)) * 8192 + t; const u32x4 w = pack8(v0, v1);
;                     vp[0] = (bf16_t)(w.x & 0xffff); vp[8192] = (bf16_t)(w.x >> 16); vp[2 * 8192] = (bf16_t)(w.y & 0xffff); vp[3 * 8192] = (bf16_t)(w.y >> 16);
;                     vp[4 * 8192] = (bf16_t)(w.z & 0xffff); vp[5 * 8192] = (bf16_t)(w.z >> 16); vp[6 * 8192] = (bf16_t)(w.w & 0xffff); vp[7 * 8192] = (bf16_t)(w.w >> 16); } } EPI_END
.LBB0_889:
	s_or_b64 exec, exec, s[18:19]
	v_or_b32_e32 v155, 0x80, v156
	v_cmp_lt_i32_e64 s[46:47], s97, v155
	s_nop 1
	v_mov_b32_e32 v128, v198
	v_mov_b32_e32 v129, v199
	v_mov_b32_e32 v130, v200
	v_mov_b32_e32 v131, v201
	v_mov_b32_e32 v166, v202
	v_mov_b32_e32 v167, v203
	v_mov_b32_e32 v168, v204
	v_mov_b32_e32 v169, v205
	v_pk_add_f32 v[162:163], v[118:119], v[130:131]
	v_pk_add_f32 v[128:129], v[116:117], v[128:129]
	v_pk_add_f32 v[160:161], v[114:115], v[168:169]
	v_pk_add_f32 v[130:131], v[112:113], v[166:167]
	s_and_saveexec_b64 s[18:19], s[46:47]
	s_xor_b64 s[18:19], exec, s[18:19]
	s_cbranch_execz .LBB0_894
	s_cmpk_lt_u32 s41, 0x900
	s_mov_b64 s[20:21], -1
	s_cbranch_scc1 .LBB0_892
	v_add_u32_e32 v132, s22, v155
	v_ashrrev_i32_e32 v133, 31, v132
	v_lshlrev_b64 v[132:133], 14, v[132:133]
	v_lshl_add_u64 v[132:133], s[70:71], 0, v[132:133]
	v_lshlrev_b32_e32 v180, 1, v164
	v_lshl_add_u64 v[132:133], v[132:133], 0, v[180:181]
	v_add_co_u32_e32 v164, vcc, s1, v132
	v_cvt_pk_bf16_f32 v159, v128, v129
	v_cvt_pk_bf16_f32 v166, v162, v163
	v_cvt_pk_bf16_f32 v167, v130, v131
	v_cvt_pk_bf16_f32 v168, v160, v161
	s_nop 1
	v_addc_co_u32_e32 v165, vcc, 0, v133, vcc
	global_store_short_d16_hi v[164:165], v159, off
	v_add_co_u32_e32 v164, vcc, s96, v132
	s_mov_b32 s20, 0xc000
	s_nop 0
	v_addc_co_u32_e32 v165, vcc, 0, v133, vcc
	global_store_short v[164:165], v166, off
	v_add_co_u32_e32 v164, vcc, s20, v132
	s_mov_b32 s20, 0x10000
	s_nop 0
	v_addc_co_u32_e32 v165, vcc, 0, v133, vcc
	global_store_short_d16_hi v[164:165], v166, off
	v_add_co_u32_e32 v164, vcc, s20, v132
	global_store_short v[132:133], v159, off
	s_nop 0
	v_addc_co_u32_e32 v165, vcc, 0, v133, vcc
	global_store_short v[164:165], v167, off
	v_add_co_u32_e32 v164, vcc, 0x14000, v132
	s_mov_b64 s[20:21], 0
	s_nop 0
	v_addc_co_u32_e32 v165, vcc, 0, v133, vcc
	global_store_short_d16_hi v[164:165], v167, off
	v_add_co_u32_e32 v164, vcc, 0x18000, v132
	s_nop 1
	v_addc_co_u32_e32 v165, vcc, 0, v133, vcc
	v_add_co_u32_e32 v132, vcc, 0x1c000, v132
	global_store_short v[164:165], v168, off
	s_nop 0
	v_addc_co_u32_e32 v133, vcc, 0, v133, vcc
	global_store_short_d16_hi v[132:133], v168, off

; __device__ __forceinline__ u32x4 pack8(f32x4 a, f32x4 b) { u32x4 w; w.x = cvt_pk_bf16(a[0], a[1]); w.y = cvt_pk_bf16(a[2], a[3]); w.z = cvt_pk_bf16(b[0], b[1]); w.w = cvt_pk_bf16(b[2], b[3]); return w; }
; #define EPI_END } asm volatile("" ::: "memory"); }
;     __device__ __forceinline__ void operator()(const f32x4 (&acc)[2][2][4][2], const pg8::Unit& u, int wr, int wc, int fr, int fq) const {
;     ...
;             EPI_BEGIN { v0 += *(const f32x4*)(bias + col); v1 += *(const f32x4*)(bias + col + 4);
;                 if (col < 2048) { *(u32x4*)(o0 + (size_t)row * 2048 + col) = pack8(v0 * qs, v1 * qs); }
;                 else if (col < 2304) { *(u32x4*)(o1 + (size_t)row * 256 + (col - 2048)) = pack8(v0, v1); }
;                 else { const int d = col - 2304, b = row >> 13, t = row & 8191; bf16_t* vp = o2 + ((size_t)(b * 256 + d)) * 8192 + t; const u32x4 w = pack8(v0, v1);
;                     vp[0] = (bf16_t)(w.x & 0xffff); vp[8192] = (bf16_t)(w.x >> 16); vp[2 * 8192] = (bf16_t)(w.y & 0xffff); vp[3 * 8192] = (bf16_t)(w.y >> 16);
;                     vp[4 * 8192] = (bf16_t)(w.z & 0xffff); vp[5 * 8192] = (bf16_t)(w.z >> 16); vp[6 * 8192] = (bf16_t)(w.w & 0xffff); vp[7 * 8192] = (bf16_t)(w.w >> 16); } } EPI_END
.LBB0_896:
	s_or_b64 exec, exec, s[18:19]
	v_or_b32_e32 v160, 16, v158
	s_movk_i32 s18, 0x1fdf
	v_ashrrev_i32_e32 v161, 31, v160
	v_bitop3_b32 v159, v158, s18, 16 bitop3:0xc8
	v_lshlrev_b64 v[136:137], 9, v[160:161]
	s_nop 1
	v_mov_b32_e32 v128, v190
	v_mov_b32_e32 v129, v191
	v_mov_b32_e32 v130, v192
	v_mov_b32_e32 v131, v193
	v_mov_b32_e32 v166, v194
	v_mov_b32_e32 v167, v195
	v_mov_b32_e32 v168, v196
	v_mov_b32_e32 v169, v197
	v_pk_add_f32 v[164:165], v[110:111], v[130:131]
	v_pk_add_f32 v[128:129], v[108:109], v[128:129]
	v_pk_add_f32 v[162:163], v[106:107], v[168:169]
	v_pk_add_f32 v[130:131], v[104:105], v[166:167]
	s_and_saveexec_b64 s[18:19], s[44:45]
	s_xor_b64 s[18:19], exec, s[18:19]
	s_cbranch_execz .LBB0_901
	s_cmpk_lt_u32 s41, 0x900
	s_mov_b64 s[20:21], -1
	s_cbranch_scc1 .LBB0_899
	v_add_u32_e32 v132, s22, v156
	v_ashrrev_i32_e32 v133, 31, v132
	v_lshlrev_b64 v[132:133], 14, v[132:133]
	v_lshl_add_u64 v[132:133], s[70:71], 0, v[132:133]
	v_lshlrev_b32_e32 v180, 1, v159
	v_lshl_add_u64 v[132:133], v[132:133], 0, v[180:181]
	v_add_co_u32_e32 v166, vcc, s1, v132
	v_cvt_pk_bf16_f32 v168, v128, v129
	v_cvt_pk_bf16_f32 v169, v164, v165
	v_cvt_pk_bf16_f32 v170, v130, v131
	v_cvt_pk_bf16_f32 v171, v162, v163
	s_nop 1
	v_addc_co_u32_e32 v167, vcc, 0, v133, vcc
	global_store_short_d16_hi v[166:167], v168, off
	v_add_co_u32_e32 v166, vcc, s96, v132
	s_mov_b32 s20, 0xc000
	s_nop 0
	v_addc_co_u32_e32 v167, vcc, 0, v133, vcc
	global_store_short v[166:167], v169, off
	v_add_co_u32_e32 v166, vcc, s20, v132
	s_mov_b32 s20, 0x10000
	s_nop 0
	v_addc_co_u32_e32 v167, vcc, 0, v133, vcc
	global_store_short_d16_hi v[166:167], v169, off
	v_add_co_u32_e32 v166, vcc, s20, v132
	global_store_short v[132:133], v168, off
	s_nop 0
	v_addc_co_u32_e32 v167, vcc, 0, v133, vcc
	global_store_short v[166:167], v170, off
	v_add_co_u32_e32 v166, vcc, 0x14000, v132
	s_mov_b64 s[20:21], 0
	s_nop 0
	v_addc_co_u32_e32 v167, vcc, 0, v133, vcc
	global_store_short_d16_hi v[166:167], v170, off
	v_add_co_u32_e32 v166, vcc, 0x18000, v132
	s_nop 1
	v_addc_co_u32_e32 v167, vcc, 0, v133, vcc
	v_add_co_u32_e32 v132, vcc, 0x1c000, v132
	global_store_short v[166:167], v171, off
	s_nop 0
	v_addc_co_u32_e32 v133, vcc, 0, v133, vcc
	global_store_short_d16_hi v[132:133], v171, off

; __device__ __forceinline__ u32x4 pack8(f32x4 a, f32x4 b) { u32x4 w; w.x = cvt_pk_bf16(a[0], a[1]); w.y = cvt_pk_bf16(a[2], a[3]); w.z = cvt_pk_bf16(b[0], b[1]); w.w = cvt_pk_bf16(b[2], b[3]); return w; }
; #define EPI_END } asm volatile("" ::: "memory"); }
;     __device__ __forceinline__ void operator()(const f32x4 (&acc)[2][2][4][2], const pg8::Unit& u, int wr, int wc, int fr, int fq) const {
;     ...
;             EPI_BEGIN { v0 += *(const f32x4*)(bias + col); v1 += *(const f32x4*)(bias + col + 4);
;                 if (col < 2048) { *(u32x4*)(o0 + (size_t)row * 2048 + col) = pack8(v0 * qs, v1 * qs); }
;                 else if (col < 2304) { *(u32x4*)(o1 + (size_t)row * 256 + (col - 2048)) = pack8(v0, v1); }
;                 else { const int d = col - 2304, b = row >> 13, t = row & 8191; bf16_t* vp = o2 + ((size_t)(b * 256 + d)) * 8192 + t; const u32x4 w = pack8(v0, v1);
;                     vp[0] = (bf16_t)(w.x & 0xffff); vp[8192] = (bf16_t)(w.x >> 16); vp[2 * 8192] = (bf16_t)(w.y & 0xffff); vp[3 * 8192] = (bf16_t)(w.y >> 16);
;                     vp[4 * 8192] = (bf16_t)(w.z & 0xffff); vp[5 * 8192] = (bf16_t)(w.z >> 16); vp[6 * 8192] = (bf16_t)(w.w & 0xffff); vp[7 * 8192] = (bf16_t)(w.w >> 16); } } EPI_END
.LBB0_903:
	s_or_b64 exec, exec, s[18:19]
	s_nop 1
	v_mov_b32_e32 v128, v198
	v_mov_b32_e32 v129, v199
	v_mov_b32_e32 v130, v200
	v_mov_b32_e32 v131, v201
	v_mov_b32_e32 v164, v202
	v_mov_b32_e32 v165, v203
	v_mov_b32_e32 v166, v204
	v_mov_b32_e32 v167, v205
	v_pk_add_f32 v[162:163], v[102:103], v[130:131]
	v_pk_add_f32 v[128:129], v[100:101], v[128:129]
	v_pk_add_f32 v[160:161], v[98:99], v[166:167]
	v_pk_add_f32 v[130:131], v[96:97], v[164:165]
	s_and_saveexec_b64 s[18:19], s[46:47]
	s_xor_b64 s[18:19], exec, s[18:19]
	s_cbranch_execz .LBB0_908
	s_cmpk_lt_u32 s41, 0x900
	s_mov_b64 s[20:21], -1
	s_cbranch_scc1 .LBB0_906
	v_add_u32_e32 v132, s22, v155
	v_ashrrev_i32_e32 v133, 31, v132
	v_lshlrev_b64 v[132:133], 14, v[132:133]
	v_lshl_add_u64 v[132:133], s[70:71], 0, v[132:133]
	v_lshlrev_b32_e32 v180, 1, v159
	v_lshl_add_u64 v[132:133], v[132:133], 0, v[180:181]
	v_add_co_u32_e32 v164, vcc, s1, v132
	v_cvt_pk_bf16_f32 v159, v128, v129
	v_cvt_pk_bf16_f32 v166, v162, v163
	v_cvt_pk_bf16_f32 v167, v130, v131
	v_cvt_pk_bf16_f32 v168, v160, v161
	s_nop 1
	v_addc_co_u32_e32 v165, vcc, 0, v133, vcc
	global_store_short_d16_hi v[164:165], v159, off
	v_add_co_u32_e32 v164, vcc, s96, v132
	s_mov_b32 s20, 0xc000
	s_nop 0
	v_addc_co_u32_e32 v165, vcc, 0, v133, vcc
	global_store_short v[164:165], v166, off
	v_add_co_u32_e32 v164, vcc, s20, v132
	s_mov_b32 s20, 0x10000
	s_nop 0
	v_addc_co_u32_e32 v165, vcc, 0, v133, vcc
	global_store_short_d16_hi v[164:165], v166, off
	v_add_co_u32_e32 v164, vcc, s20, v132
	global_store_short v[132:133], v159, off
	s_nop 0
	v_addc_co_u32_e32 v165, vcc, 0, v133, vcc
	global_store_short v[164:165], v167, off
	v_add_co_u32_e32 v164, vcc, 0x14000, v132
	s_mov_b64 s[20:21], 0
	s_nop 0
	v_addc_co_u32_e32 v165, vcc, 0, v133, vcc
	global_store_short_d16_hi v[164:165], v167, off
	v_add_co_u32_e32 v164, vcc, 0x18000, v132
	s_nop 1
	v_addc_co_u32_e32 v165, vcc, 0, v133, vcc
	v_add_co_u32_e32 v132, vcc, 0x1c000, v132
	global_store_short v[164:165], v168, off
	s_nop 0
	v_addc_co_u32_e32 v133, vcc, 0, v133, vcc
	global_store_short_d16_hi v[132:133], v168, off

; __device__ __forceinline__ u32x4 pack8(f32x4 a, f32x4 b) { u32x4 w; w.x = cvt_pk_bf16(a[0], a[1]); w.y = cvt_pk_bf16(a[2], a[3]); w.z = cvt_pk_bf16(b[0], b[1]); w.w = cvt_pk_bf16(b[2], b[3]); return w; }
; #define EPI_END } asm volatile("" ::: "memory"); }
;     __device__ __forceinline__ void operator()(const f32x4 (&acc)[2][2][4][2], const pg8::Unit& u, int wr, int wc, int fr, int fq) const {
;     ...
;             EPI_BEGIN { v0 += *(const f32x4*)(bias + col); v1 += *(const f32x4*)(bias + col + 4);
;                 if (col < 2048) { *(u32x4*)(o0 + (size_t)row * 2048 + col) = pack8(v0 * qs, v1 * qs); }
;                 else if (col < 2304) { *(u32x4*)(o1 + (size_t)row * 256 + (col - 2048)) = pack8(v0, v1); }
;                 else { const int d = col - 2304, b = row >> 13, t = row & 8191; bf16_t* vp = o2 + ((size_t)(b * 256 + d)) * 8192 + t; const u32x4 w = pack8(v0, v1);
;                     vp[0] = (bf16_t)(w.x & 0xffff); vp[8192] = (bf16_t)(w.x >> 16); vp[2 * 8192] = (bf16_t)(w.y & 0xffff); vp[3 * 8192] = (bf16_t)(w.y >> 16);
;                     vp[4 * 8192] = (bf16_t)(w.z & 0xffff); vp[5 * 8192] = (bf16_t)(w.z >> 16); vp[6 * 8192] = (bf16_t)(w.w & 0xffff); vp[7 * 8192] = (bf16_t)(w.w >> 16); } } EPI_END
.LBB0_910:
	s_or_b64 exec, exec, s[18:19]
	v_or_b32_e32 v160, 32, v158
	s_movk_i32 s18, 0x1fef
	v_ashrrev_i32_e32 v161, 31, v160
	v_bitop3_b32 v159, v158, s18, 32 bitop3:0xc8
	v_lshlrev_b64 v[136:137], 9, v[160:161]
	s_nop 1
	v_mov_b32_e32 v128, v190
	v_mov_b32_e32 v129, v191
	v_mov_b32_e32 v130, v192
	v_mov_b32_e32 v131, v193
	v_mov_b32_e32 v166, v194
	v_mov_b32_e32 v167, v195
	v_mov_b32_e32 v168, v196
	v_mov_b32_e32 v169, v197
	v_pk_add_f32 v[164:165], v[94:95], v[130:131]
	v_pk_add_f32 v[128:129], v[92:93], v[128:129]
	v_pk_add_f32 v[162:163], v[90:91], v[168:169]
	v_pk_add_f32 v[130:131], v[88:89], v[166:167]
	s_and_saveexec_b64 s[18:19], s[44:45]
	s_xor_b64 s[18:19], exec, s[18:19]
	s_cbranch_execz .LBB0_915
	s_cmpk_lt_u32 s41, 0x900
	s_mov_b64 s[20:21], -1
	s_cbranch_scc1 .LBB0_913
	v_add_u32_e32 v132, s22, v156
	v_ashrrev_i32_e32 v133, 31, v132
	v_lshlrev_b64 v[132:133], 14, v[132:133]
	v_lshl_add_u64 v[132:133], s[70:71], 0, v[132:133]
	v_lshlrev_b32_e32 v180, 1, v159
	v_lshl_add_u64 v[132:133], v[132:133], 0, v[180:181]
	v_add_co_u32_e32 v166, vcc, s1, v132
	v_cvt_pk_bf16_f32 v168, v128, v129
	v_cvt_pk_bf16_f32 v169, v164, v165
	v_cvt_pk_bf16_f32 v170, v130, v131
	v_cvt_pk_bf16_f32 v171, v162, v163
	s_nop 1
	v_addc_co_u32_e32 v167, vcc, 0, v133, vcc
	global_store_short_d16_hi v[166:167], v168, off
	v_add_co_u32_e32 v166, vcc, s96, v132
	s_mov_b32 s20, 0xc000
	s_nop 0
	v_addc_co_u32_e32 v167, vcc, 0, v133, vcc
	global_store_short v[166:167], v169, off
	v_add_co_u32_e32 v166, vcc, s20, v132
	s_mov_b32 s20, 0x10000
	s_nop 0
	v_addc_co_u32_e32 v167, vcc, 0, v133, vcc
	global_store_short_d16_hi v[166:167], v169, off
	v_add_co_u32_e32 v166, vcc, s20, v132
	global_store_short v[132:133], v168, off
	s_nop 0
	v_addc_co_u32_e32 v167, vcc, 0, v133, vcc
	global_store_short v[166:167], v170, off
	v_add_co_u32_e32 v166, vcc, 0x14000, v132
	s_mov_b64 s[20:21], 0
	s_nop 0
	v_addc_co_u32_e32 v167, vcc, 0, v133, vcc
	global_store_short_d16_hi v[166:167], v170, off
	v_add_co_u32_e32 v166, vcc, 0x18000, v132
	s_nop 1
	v_addc_co_u32_e32 v167, vcc, 0, v133, vcc
	v_add_co_u32_e32 v132, vcc, 0x1c000, v132
	global_store_short v[166:167], v171, off
	s_nop 0
	v_addc_co_u32_e32 v133, vcc, 0, v133, vcc
	global_store_short_d16_hi v[132:133], v171, off

; __device__ __forceinline__ u32x4 pack8(f32x4 a, f32x4 b) { u32x4 w; w.x = cvt_pk_bf16(a[0], a[1]); w.y = cvt_pk_bf16(a[2], a[3]); w.z = cvt_pk_bf16(b[0], b[1]); w.w = cvt_pk_bf16(b[2], b[3]); return w; }
; #define EPI_END } asm volatile("" ::: "memory"); }
;     __device__ __forceinline__ void operator()(const f32x4 (&acc)[2][2][4][2], const pg8::Unit& u, int wr, int wc, int fr, int fq) const {
;     ...
;             EPI_BEGIN { v0 += *(const f32x4*)(bias + col); v1 += *(const f32x4*)(bias + col + 4);
;                 if (col < 2048) { *(u32x4*)(o0 + (size_t)row * 2048 + col) = pack8(v0 * qs, v1 * qs); }
;                 else if (col < 2304) { *(u32x4*)(o1 + (size_t)row * 256 + (col - 2048)) = pack8(v0, v1); }
;                 else { const int d = col - 2304, b = row >> 13, t = row & 8191; bf16_t* vp = o2 + ((size_t)(b * 256 + d)) * 8192 + t; const u32x4 w = pack8(v0, v1);
;                     vp[0] = (bf16_t)(w.x & 0xffff); vp[8192] = (bf16_t)(w.x >> 16); vp[2 * 8192] = (bf16_t)(w.y & 0xffff); vp[3 * 8192] = (bf16_t)(w.y >> 16);
;                     vp[4 * 8192] = (bf16_t)(w.z & 0xffff); vp[5 * 8192] = (bf16_t)(w.z >> 16); vp[6 * 8192] = (bf16_t)(w.w & 0xffff); vp[7 * 8192] = (bf16_t)(w.w >> 16); } } EPI_END
.LBB0_917:
	s_or_b64 exec, exec, s[18:19]
	s_nop 1
	v_mov_b32_e32 v128, v198
	v_mov_b32_e32 v129, v199
	v_mov_b32_e32 v130, v200
	v_mov_b32_e32 v131, v201
	v_mov_b32_e32 v164, v202
	v_mov_b32_e32 v165, v203
	v_mov_b32_e32 v166, v204
	v_mov_b32_e32 v167, v205
	v_pk_add_f32 v[162:163], v[86:87], v[130:131]
	v_pk_add_f32 v[128:129], v[84:85], v[128:129]
	v_pk_add_f32 v[160:161], v[82:83], v[166:167]
	v_pk_add_f32 v[130:131], v[80:81], v[164:165]
	s_and_saveexec_b64 s[18:19], s[46:47]
	s_xor_b64 s[18:19], exec, s[18:19]
	s_cbranch_execz .LBB0_922
	s_cmpk_lt_u32 s41, 0x900
	s_mov_b64 s[20:21], -1
	s_cbranch_scc1 .LBB0_920
	v_add_u32_e32 v132, s22, v155
	v_ashrrev_i32_e32 v133, 31, v132
	v_lshlrev_b64 v[132:133], 14, v[132:133]
	v_lshl_add_u64 v[132:133], s[70:71], 0, v[132:133]
	v_lshlrev_b32_e32 v180, 1, v159
	v_lshl_add_u64 v[132:133], v[132:133], 0, v[180:181]
	v_add_co_u32_e32 v164, vcc, s1, v132
	v_cvt_pk_bf16_f32 v159, v128, v129
	v_cvt_pk_bf16_f32 v166, v162, v163
	v_cvt_pk_bf16_f32 v167, v130, v131
	v_cvt_pk_bf16_f32 v168, v160, v161
	s_nop 1
	v_addc_co_u32_e32 v165, vcc, 0, v133, vcc
	global_store_short_d16_hi v[164:165], v159, off
	v_add_co_u32_e32 v164, vcc, s96, v132
	s_mov_b32 s20, 0xc000
	s_nop 0
	v_addc_co_u32_e32 v165, vcc, 0, v133, vcc
	global_store_short v[164:165], v166, off
	v_add_co_u32_e32 v164, vcc, s20, v132
	s_mov_b32 s20, 0x10000
	s_nop 0
	v_addc_co_u32_e32 v165, vcc, 0, v133, vcc
	global_store_short_d16_hi v[164:165], v166, off
	v_add_co_u32_e32 v164, vcc, s20, v132
	global_store_short v[132:133], v159, off
	s_nop 0
	v_addc_co_u32_e32 v165, vcc, 0, v133, vcc
	global_store_short v[164:165], v167, off
	v_add_co_u32_e32 v164, vcc, 0x14000, v132
	s_mov_b64 s[20:21], 0
	s_nop 0
	v_addc_co_u32_e32 v165, vcc, 0, v133, vcc
	global_store_short_d16_hi v[164:165], v167, off
	v_add_co_u32_e32 v164, vcc, 0x18000, v132
	s_nop 1
	v_addc_co_u32_e32 v165, vcc, 0, v133, vcc
	v_add_co_u32_e32 v132, vcc, 0x1c000, v132
	global_store_short v[164:165], v168, off
	s_nop 0
	v_addc_co_u32_e32 v133, vcc, 0, v133, vcc
	global_store_short_d16_hi v[132:133], v168, off

; __device__ __forceinline__ u32x4 pack8(f32x4 a, f32x4 b) { u32x4 w; w.x = cvt_pk_bf16(a[0], a[1]); w.y = cvt_pk_bf16(a[2], a[3]); w.z = cvt_pk_bf16(b[0], b[1]); w.w = cvt_pk_bf16(b[2], b[3]); return w; }
; #define EPI_END } asm volatile("" ::: "memory"); }
;     __device__ __forceinline__ void operator()(const f32x4 (&acc)[2][2][4][2], const pg8::Unit& u, int wr, int wc, int fr, int fq) const {
;     ...
;             EPI_BEGIN { v0 += *(const f32x4*)(bias + col); v1 += *(const f32x4*)(bias + col + 4);
;                 if (col < 2048) { *(u32x4*)(o0 + (size_t)row * 2048 + col) = pack8(v0 * qs, v1 * qs); }
;                 else if (col < 2304) { *(u32x4*)(o1 + (size_t)row * 256 + (col - 2048)) = pack8(v0, v1); }
;                 else { const int d = col - 2304, b = row >> 13, t = row & 8191; bf16_t* vp = o2 + ((size_t)(b * 256 + d)) * 8192 + t; const u32x4 w = pack8(v0, v1);
;                     vp[0] = (bf16_t)(w.x & 0xffff); vp[8192] = (bf16_t)(w.x >> 16); vp[2 * 8192] = (bf16_t)(w.y & 0xffff); vp[3 * 8192] = (bf16_t)(w.y >> 16);
;                     vp[4 * 8192] = (bf16_t)(w.z & 0xffff); vp[5 * 8192] = (bf16_t)(w.z >> 16); vp[6 * 8192] = (bf16_t)(w.w & 0xffff); vp[7 * 8192] = (bf16_t)(w.w >> 16); } } EPI_END
.LBB0_924:
	s_or_b64 exec, exec, s[18:19]
	v_or_b32_e32 v160, 48, v158
	s_movk_i32 s18, 0x1fff
	v_ashrrev_i32_e32 v161, 31, v160
	v_bitop3_b32 v159, v158, s18, 48 bitop3:0xc8
	v_lshlrev_b64 v[136:137], 9, v[160:161]
	s_nop 1
	v_mov_b32_e32 v128, v190
	v_mov_b32_e32 v129, v191
	v_mov_b32_e32 v130, v192
	v_mov_b32_e32 v131, v193
	v_mov_b32_e32 v166, v194
	v_mov_b32_e32 v167, v195
	v_mov_b32_e32 v168, v196
	v_mov_b32_e32 v169, v197
	v_pk_add_f32 v[164:165], v[78:79], v[130:131]
	v_pk_add_f32 v[128:129], v[76:77], v[128:129]
	v_pk_add_f32 v[162:163], v[74:75], v[168:169]
	v_pk_add_f32 v[130:131], v[72:73], v[166:167]
	s_and_saveexec_b64 s[18:19], s[44:45]
	s_xor_b64 s[18:19], exec, s[18:19]
	s_cbranch_execz .LBB0_929
	s_cmpk_lt_u32 s41, 0x900
	s_mov_b64 s[20:21], -1
	s_cbranch_scc1 .LBB0_927
	v_add_u32_e32 v132, s22, v156
	v_ashrrev_i32_e32 v133, 31, v132
	v_lshlrev_b64 v[132:133], 14, v[132:133]
	v_lshl_add_u64 v[132:133], s[70:71], 0, v[132:133]
	v_lshlrev_b32_e32 v180, 1, v159
	v_lshl_add_u64 v[132:133], v[132:133], 0, v[180:181]
	v_add_co_u32_e32 v166, vcc, s1, v132
	v_cvt_pk_bf16_f32 v168, v128, v129
	v_cvt_pk_bf16_f32 v169, v164, v165
	v_cvt_pk_bf16_f32 v170, v130, v131
	v_cvt_pk_bf16_f32 v171, v162, v163
	s_nop 1
	v_addc_co_u32_e32 v167, vcc, 0, v133, vcc
	global_store_short_d16_hi v[166:167], v168, off
	v_add_co_u32_e32 v166, vcc, s96, v132
	s_mov_b32 s20, 0xc000
	s_nop 0
	v_addc_co_u32_e32 v167, vcc, 0, v133, vcc
	global_store_short v[166:167], v169, off
	v_add_co_u32_e32 v166, vcc, s20, v132
	s_mov_b32 s20, 0x10000
	s_nop 0
	v_addc_co_u32_e32 v167, vcc, 0, v133, vcc
	global_store_short_d16_hi v[166:167], v169, off
	v_add_co_u32_e32 v166, vcc, s20, v132
	global_store_short v[132:133], v168, off
	s_nop 0
	v_addc_co_u32_e32 v167, vcc, 0, v133, vcc
	global_store_short v[166:167], v170, off
	v_add_co_u32_e32 v166, vcc, 0x14000, v132
	s_mov_b64 s[20:21], 0
	s_nop 0
	v_addc_co_u32_e32 v167, vcc, 0, v133, vcc
	global_store_short_d16_hi v[166:167], v170, off
	v_add_co_u32_e32 v166, vcc, 0x18000, v132
	s_nop 1
	v_addc_co_u32_e32 v167, vcc, 0, v133, vcc
	v_add_co_u32_e32 v132, vcc, 0x1c000, v132
	global_store_short v[166:167], v171, off
	s_nop 0
	v_addc_co_u32_e32 v133, vcc, 0, v133, vcc
	global_store_short_d16_hi v[132:133], v171, off

; __device__ __forceinline__ u32x4 pack8(f32x4 a, f32x4 b) { u32x4 w; w.x = cvt_pk_bf16(a[0], a[1]); w.y = cvt_pk_bf16(a[2], a[3]); w.z = cvt_pk_bf16(b[0], b[1]); w.w = cvt_pk_bf16(b[2], b[3]); return w; }
; #define EPI_END } asm volatile("" ::: "memory"); }
;     __device__ __forceinline__ void operator()(const f32x4 (&acc)[2][2][4][2], const pg8::Unit& u, int wr, int wc, int fr, int fq) const {
;     ...
;             EPI_BEGIN { v0 += *(const f32x4*)(bias + col); v1 += *(const f32x4*)(bias + col + 4);
;                 if (col < 2048) { *(u32x4*)(o0 + (size_t)row * 2048 + col) = pack8(v0 * qs, v1 * qs); }
;                 else if (col < 2304) { *(u32x4*)(o1 + (size_t)row * 256 + (col - 2048)) = pack8(v0, v1); }
;                 else { const int d = col - 2304, b = row >> 13, t = row & 8191; bf16_t* vp = o2 + ((size_t)(b * 256 + d)) * 8192 + t; const u32x4 w = pack8(v0, v1);
;                     vp[0] = (bf16_t)(w.x & 0xffff); vp[8192] = (bf16_t)(w.x >> 16); vp[2 * 8192] = (bf16_t)(w.y & 0xffff); vp[3 * 8192] = (bf16_t)(w.y >> 16);
;                     vp[4 * 8192] = (bf16_t)(w.z & 0xffff); vp[5 * 8192] = (bf16_t)(w.z >> 16); vp[6 * 8192] = (bf16_t)(w.w & 0xffff); vp[7 * 8192] = (bf16_t)(w.w >> 16); } } EPI_END
.LBB0_931:
	s_or_b64 exec, exec, s[18:19]
	s_nop 1
	v_mov_b32_e32 v128, v198
	v_mov_b32_e32 v129, v199
	v_mov_b32_e32 v130, v200
	v_mov_b32_e32 v131, v201
	v_mov_b32_e32 v164, v202
	v_mov_b32_e32 v165, v203
	v_mov_b32_e32 v166, v204
	v_mov_b32_e32 v167, v205
	v_pk_add_f32 v[162:163], v[70:71], v[130:131]
	v_pk_add_f32 v[128:129], v[68:69], v[128:129]
	v_pk_add_f32 v[160:161], v[66:67], v[166:167]
	v_pk_add_f32 v[130:131], v[64:65], v[164:165]
	s_and_saveexec_b64 s[18:19], s[46:47]
	s_xor_b64 s[18:19], exec, s[18:19]
	s_cbranch_execz .LBB0_936
	s_cmpk_lt_u32 s41, 0x900
	s_mov_b64 s[20:21], -1
	s_cbranch_scc1 .LBB0_934
	v_add_u32_e32 v132, s22, v155
	v_ashrrev_i32_e32 v133, 31, v132
	v_lshlrev_b64 v[132:133], 14, v[132:133]
	v_lshl_add_u64 v[132:133], s[70:71], 0, v[132:133]
	v_lshlrev_b32_e32 v180, 1, v159
	v_lshl_add_u64 v[132:133], v[132:133], 0, v[180:181]
	v_add_co_u32_e32 v164, vcc, s1, v132
	v_cvt_pk_bf16_f32 v159, v128, v129
	v_cvt_pk_bf16_f32 v166, v162, v163
	v_cvt_pk_bf16_f32 v167, v130, v131
	v_cvt_pk_bf16_f32 v168, v160, v161
	s_nop 1
	v_addc_co_u32_e32 v165, vcc, 0, v133, vcc
	global_store_short_d16_hi v[164:165], v159, off
	v_add_co_u32_e32 v164, vcc, s96, v132
	s_mov_b32 s20, 0xc000
	s_nop 0
	v_addc_co_u32_e32 v165, vcc, 0, v133, vcc
	global_store_short v[164:165], v166, off
	v_add_co_u32_e32 v164, vcc, s20, v132
	s_mov_b32 s20, 0x10000
	s_nop 0
	v_addc_co_u32_e32 v165, vcc, 0, v133, vcc
	global_store_short_d16_hi v[164:165], v166, off
	v_add_co_u32_e32 v164, vcc, s20, v132
	global_store_short v[132:133], v159, off
	s_nop 0
	v_addc_co_u32_e32 v165, vcc, 0, v133, vcc
	global_store_short v[164:165], v167, off
	v_add_co_u32_e32 v164, vcc, 0x14000, v132
	s_mov_b64 s[20:21], 0
	s_nop 0
	v_addc_co_u32_e32 v165, vcc, 0, v133, vcc
	global_store_short_d16_hi v[164:165], v167, off
	v_add_co_u32_e32 v164, vcc, 0x18000, v132
	s_nop 1
	v_addc_co_u32_e32 v165, vcc, 0, v133, vcc
	v_add_co_u32_e32 v132, vcc, 0x1c000, v132
	global_store_short v[164:165], v168, off
	s_nop 0
	v_addc_co_u32_e32 v133, vcc, 0, v133, vcc
	global_store_short_d16_hi v[132:133], v168, off

; __device__ __forceinline__ u32x4 pack8(f32x4 a, f32x4 b) { u32x4 w; w.x = cvt_pk_bf16(a[0], a[1]); w.y = cvt_pk_bf16(a[2], a[3]); w.z = cvt_pk_bf16(b[0], b[1]); w.w = cvt_pk_bf16(b[2], b[3]); return w; }
; #define EPI_END } asm volatile("" ::: "memory"); }
;     __device__ __forceinline__ void operator()(const f32x4 (&acc)[2][2][4][2], const pg8::Unit& u, int wr, int wc, int fr, int fq) const {
;     ...
;             EPI_BEGIN { v0 += *(const f32x4*)(bias + col); v1 += *(const f32x4*)(bias + col + 4);
;                 if (col < 2048) { *(u32x4*)(o0 + (size_t)row * 2048 + col) = pack8(v0 * qs, v1 * qs); }
;                 else if (col < 2304) { *(u32x4*)(o1 + (size_t)row * 256 + (col - 2048)) = pack8(v0, v1); }
;                 else { const int d = col - 2304, b = row >> 13, t = row & 8191; bf16_t* vp = o2 + ((size_t)(b * 256 + d)) * 8192 + t; const u32x4 w = pack8(v0, v1);
;                     vp[0] = (bf16_t)(w.x & 0xffff); vp[8192] = (bf16_t)(w.x >> 16); vp[2 * 8192] = (bf16_t)(w.y & 0xffff); vp[3 * 8192] = (bf16_t)(w.y >> 16);
;                     vp[4 * 8192] = (bf16_t)(w.z & 0xffff); vp[5 * 8192] = (bf16_t)(w.z >> 16); vp[6 * 8192] = (bf16_t)(w.w & 0xffff); vp[7 * 8192] = (bf16_t)(w.w >> 16); } } EPI_END
.LBB0_938:
	s_or_b64 exec, exec, s[18:19]
	v_add_u32_e32 v160, 0x80, v158
	v_ashrrev_i32_e32 v132, 5, v160
	v_ashrrev_i32_e32 v161, 31, v160
	v_and_b32_e32 v132, 0xffffff00, v132
	v_and_b32_e32 v166, 0x1fcf, v160
	v_lshlrev_b64 v[136:137], 9, v[160:161]
	v_add_u32_e32 v159, 0xfffff700, v132
	s_nop 1
	v_mov_b32_e32 v128, v190
	v_mov_b32_e32 v129, v191
	v_mov_b32_e32 v130, v192
	v_mov_b32_e32 v131, v193
	v_mov_b32_e32 v168, v194
	v_mov_b32_e32 v169, v195
	v_mov_b32_e32 v170, v196
	v_mov_b32_e32 v171, v197
	v_pk_add_f32 v[164:165], v[62:63], v[130:131]
	v_pk_add_f32 v[128:129], v[60:61], v[128:129]
	v_pk_add_f32 v[162:163], v[58:59], v[170:171]
	v_pk_add_f32 v[130:131], v[56:57], v[168:169]
	s_and_saveexec_b64 s[18:19], s[44:45]
	s_xor_b64 s[18:19], exec, s[18:19]
	s_cbranch_execz .LBB0_943
	s_cmpk_lt_u32 s41, 0x900
	s_mov_b64 s[20:21], -1
	s_cbranch_scc1 .LBB0_941
	v_add_u32_e32 v132, v159, v156
	v_ashrrev_i32_e32 v133, 31, v132
	v_lshlrev_b64 v[132:133], 14, v[132:133]
	v_lshl_add_u64 v[132:133], s[70:71], 0, v[132:133]
	v_lshlrev_b32_e32 v180, 1, v166
	v_lshl_add_u64 v[132:133], v[132:133], 0, v[180:181]
	v_add_co_u32_e32 v168, vcc, s1, v132
	v_cvt_pk_bf16_f32 v167, v128, v129
	v_cvt_pk_bf16_f32 v170, v164, v165
	v_cvt_pk_bf16_f32 v171, v130, v131
	v_cvt_pk_bf16_f32 v172, v162, v163
	s_nop 1
	v_addc_co_u32_e32 v169, vcc, 0, v133, vcc
	global_store_short_d16_hi v[168:169], v167, off
	v_add_co_u32_e32 v168, vcc, s96, v132
	s_mov_b32 s20, 0xc000
	s_nop 0
	v_addc_co_u32_e32 v169, vcc, 0, v133, vcc
	global_store_short v[168:169], v170, off
	v_add_co_u32_e32 v168, vcc, s20, v132
	s_mov_b32 s20, 0x10000
	s_nop 0
	v_addc_co_u32_e32 v169, vcc, 0, v133, vcc
	global_store_short_d16_hi v[168:169], v170, off
	v_add_co_u32_e32 v168, vcc, s20, v132
	global_store_short v[132:133], v167, off
	s_nop 0
	v_addc_co_u32_e32 v169, vcc, 0, v133, vcc
	global_store_short v[168:169], v171, off
	v_add_co_u32_e32 v168, vcc, 0x14000, v132
	s_mov_b64 s[20:21], 0
	s_nop 0
	v_addc_co_u32_e32 v169, vcc, 0, v133, vcc
	global_store_short_d16_hi v[168:169], v171, off
	v_add_co_u32_e32 v168, vcc, 0x18000, v132
	s_nop 1
	v_addc_co_u32_e32 v169, vcc, 0, v133, vcc
	v_add_co_u32_e32 v132, vcc, 0x1c000, v132
	global_store_short v[168:169], v172, off
	s_nop 0
	v_addc_co_u32_e32 v133, vcc, 0, v133, vcc
	global_store_short_d16_hi v[132:133], v172, off

; __device__ __forceinline__ u32x4 pack8(f32x4 a, f32x4 b) { u32x4 w; w.x = cvt_pk_bf16(a[0], a[1]); w.y = cvt_pk_bf16(a[2], a[3]); w.z = cvt_pk_bf16(b[0], b[1]); w.w = cvt_pk_bf16(b[2], b[3]); return w; }
; #define EPI_END } asm volatile("" ::: "memory"); }
;     __device__ __forceinline__ void operator()(const f32x4 (&acc)[2][2][4][2], const pg8::Unit& u, int wr, int wc, int fr, int fq) const {
;     ...
;             EPI_BEGIN { v0 += *(const f32x4*)(bias + col); v1 += *(const f32x4*)(bias + col + 4);
;                 if (col < 2048) { *(u32x4*)(o0 + (size_t)row * 2048 + col) = pack8(v0 * qs, v1 * qs); }
;                 else if (col < 2304) { *(u32x4*)(o1 + (size_t)row * 256 + (col - 2048)) = pack8(v0, v1); }
;                 else { const int d = col - 2304, b = row >> 13, t = row & 8191; bf16_t* vp = o2 + ((size_t)(b * 256 + d)) * 8192 + t; const u32x4 w = pack8(v0, v1);
;                     vp[0] = (bf16_t)(w.x & 0xffff); vp[8192] = (bf16_t)(w.x >> 16); vp[2 * 8192] = (bf16_t)(w.y & 0xffff); vp[3 * 8192] = (bf16_t)(w.y >> 16);
;                     vp[4 * 8192] = (bf16_t)(w.z & 0xffff); vp[5 * 8192] = (bf16_t)(w.z >> 16); vp[6 * 8192] = (bf16_t)(w.w & 0xffff); vp[7 * 8192] = (bf16_t)(w.w >> 16); } } EPI_END
.LBB0_945:
	s_or_b64 exec, exec, s[18:19]
	s_nop 1
	v_mov_b32_e32 v128, v198
	v_mov_b32_e32 v129, v199
	v_mov_b32_e32 v130, v200
	v_mov_b32_e32 v131, v201
	v_mov_b32_e32 v168, v202
	v_mov_b32_e32 v169, v203
	v_mov_b32_e32 v170, v204
	v_mov_b32_e32 v171, v205
	v_pk_add_f32 v[162:163], v[54:55], v[130:131]
	v_pk_add_f32 v[128:129], v[52:53], v[128:129]
	v_pk_add_f32 v[160:161], v[50:51], v[170:171]
	v_pk_add_f32 v[130:131], v[48:49], v[168:169]
	s_and_saveexec_b64 s[18:19], s[46:47]
	s_xor_b64 s[18:19], exec, s[18:19]
	s_cbranch_execz .LBB0_950
	s_cmpk_lt_u32 s41, 0x900
	s_mov_b64 s[20:21], -1
	s_cbranch_scc1 .LBB0_948
	v_add_u32_e32 v132, v159, v155
	v_ashrrev_i32_e32 v133, 31, v132
	v_lshlrev_b64 v[132:133], 14, v[132:133]
	v_lshl_add_u64 v[132:133], s[70:71], 0, v[132:133]
	v_lshlrev_b32_e32 v180, 1, v166
	v_lshl_add_u64 v[132:133], v[132:133], 0, v[180:181]
	v_add_co_u32_e32 v164, vcc, s1, v132
	v_cvt_pk_bf16_f32 v166, v128, v129
	v_cvt_pk_bf16_f32 v167, v162, v163
	v_cvt_pk_bf16_f32 v168, v130, v131
	v_cvt_pk_bf16_f32 v169, v160, v161
	s_nop 1
	v_addc_co_u32_e32 v165, vcc, 0, v133, vcc
	global_store_short_d16_hi v[164:165], v166, off
	v_add_co_u32_e32 v164, vcc, s96, v132
	s_mov_b32 s20, 0xc000
	s_nop 0
	v_addc_co_u32_e32 v165, vcc, 0, v133, vcc
	global_store_short v[164:165], v167, off
	v_add_co_u32_e32 v164, vcc, s20, v132
	s_mov_b32 s20, 0x10000
	s_nop 0
	v_addc_co_u32_e32 v165, vcc, 0, v133, vcc
	global_store_short_d16_hi v[164:165], v167, off
	v_add_co_u32_e32 v164, vcc, s20, v132
	global_store_short v[132:133], v166, off
	s_nop 0
	v_addc_co_u32_e32 v165, vcc, 0, v133, vcc
	global_store_short v[164:165], v168, off
	v_add_co_u32_e32 v164, vcc, 0x14000, v132
	s_mov_b64 s[20:21], 0
	s_nop 0
	v_addc_co_u32_e32 v165, vcc, 0, v133, vcc
	global_store_short_d16_hi v[164:165], v168, off
	v_add_co_u32_e32 v164, vcc, 0x18000, v132
	s_nop 1
	v_addc_co_u32_e32 v165, vcc, 0, v133, vcc
	v_add_co_u32_e32 v132, vcc, 0x1c000, v132
	global_store_short v[164:165], v169, off
	s_nop 0
	v_addc_co_u32_e32 v133, vcc, 0, v133, vcc
	global_store_short_d16_hi v[132:133], v169, off

; __device__ __forceinline__ u32x4 pack8(f32x4 a, f32x4 b) { u32x4 w; w.x = cvt_pk_bf16(a[0], a[1]); w.y = cvt_pk_bf16(a[2], a[3]); w.z = cvt_pk_bf16(b[0], b[1]); w.w = cvt_pk_bf16(b[2], b[3]); return w; }
; #define EPI_END } asm volatile("" ::: "memory"); }
;     __device__ __forceinline__ void operator()(const f32x4 (&acc)[2][2][4][2], const pg8::Unit& u, int wr, int wc, int fr, int fq) const {
;     ...
;             EPI_BEGIN { v0 += *(const f32x4*)(bias + col); v1 += *(const f32x4*)(bias + col + 4);
;                 if (col < 2048) { *(u32x4*)(o0 + (size_t)row * 2048 + col) = pack8(v0 * qs, v1 * qs); }
;                 else if (col < 2304) { *(u32x4*)(o1 + (size_t)row * 256 + (col - 2048)) = pack8(v0, v1); }
;                 else { const int d = col - 2304, b = row >> 13, t = row & 8191; bf16_t* vp = o2 + ((size_t)(b * 256 + d)) * 8192 + t; const u32x4 w = pack8(v0, v1);
;                     vp[0] = (bf16_t)(w.x & 0xffff); vp[8192] = (bf16_t)(w.x >> 16); vp[2 * 8192] = (bf16_t)(w.y & 0xffff); vp[3 * 8192] = (bf16_t)(w.y >> 16);
;                     vp[4 * 8192] = (bf16_t)(w.z & 0xffff); vp[5 * 8192] = (bf16_t)(w.z >> 16); vp[6 * 8192] = (bf16_t)(w.w & 0xffff); vp[7 * 8192] = (bf16_t)(w.w >> 16); } } EPI_END
.LBB0_952:
	s_or_b64 exec, exec, s[18:19]
	v_add_u32_e32 v160, 0x90, v158
	v_ashrrev_i32_e32 v161, 31, v160
	v_and_b32_e32 v166, 0x1fdf, v160
	v_lshlrev_b64 v[136:137], 9, v[160:161]
	s_nop 1
	v_mov_b32_e32 v128, v190
	v_mov_b32_e32 v129, v191
	v_mov_b32_e32 v130, v192
	v_mov_b32_e32 v131, v193
	v_mov_b32_e32 v168, v194
	v_mov_b32_e32 v169, v195
	v_mov_b32_e32 v170, v196
	v_mov_b32_e32 v171, v197
	v_pk_add_f32 v[164:165], v[46:47], v[130:131]
	v_pk_add_f32 v[128:129], v[44:45], v[128:129]
	v_pk_add_f32 v[162:163], v[42:43], v[170:171]
	v_pk_add_f32 v[130:131], v[40:41], v[168:169]
	s_and_saveexec_b64 s[18:19], s[44:45]
	s_xor_b64 s[18:19], exec, s[18:19]
	s_cbranch_execz .LBB0_957
	s_cmpk_lt_u32 s41, 0x900
	s_mov_b64 s[20:21], -1
	s_cbranch_scc1 .LBB0_955
	v_add_u32_e32 v132, v159, v156
	v_ashrrev_i32_e32 v133, 31, v132
	v_lshlrev_b64 v[132:133], 14, v[132:133]
	v_lshl_add_u64 v[132:133], s[70:71], 0, v[132:133]
	v_lshlrev_b32_e32 v180, 1, v166
	v_lshl_add_u64 v[132:133], v[132:133], 0, v[180:181]
	v_add_co_u32_e32 v168, vcc, s1, v132
	v_cvt_pk_bf16_f32 v167, v128, v129
	v_cvt_pk_bf16_f32 v170, v164, v165
	v_cvt_pk_bf16_f32 v171, v130, v131
	v_cvt_pk_bf16_f32 v172, v162, v163
	s_nop 1
	v_addc_co_u32_e32 v169, vcc, 0, v133, vcc
	global_store_short_d16_hi v[168:169], v167, off
	v_add_co_u32_e32 v168, vcc, s96, v132
	s_mov_b32 s20, 0xc000
	s_nop 0
	v_addc_co_u32_e32 v169, vcc, 0, v133, vcc
	global_store_short v[168:169], v170, off
	v_add_co_u32_e32 v168, vcc, s20, v132
	s_mov_b32 s20, 0x10000
	s_nop 0
	v_addc_co_u32_e32 v169, vcc, 0, v133, vcc
	global_store_short_d16_hi v[168:169], v170, off
	v_add_co_u32_e32 v168, vcc, s20, v132
	global_store_short v[132:133], v167, off
	s_nop 0
	v_addc_co_u32_e32 v169, vcc, 0, v133, vcc
	global_store_short v[168:169], v171, off
	v_add_co_u32_e32 v168, vcc, 0x14000, v132
	s_mov_b64 s[20:21], 0
	s_nop 0
	v_addc_co_u32_e32 v169, vcc, 0, v133, vcc
	global_store_short_d16_hi v[168:169], v171, off
	v_add_co_u32_e32 v168, vcc, 0x18000, v132
	s_nop 1
	v_addc_co_u32_e32 v169, vcc, 0, v133, vcc
	v_add_co_u32_e32 v132, vcc, 0x1c000, v132
	global_store_short v[168:169], v172, off
	s_nop 0
	v_addc_co_u32_e32 v133, vcc, 0, v133, vcc
	global_store_short_d16_hi v[132:133], v172, off

; __device__ __forceinline__ u32x4 pack8(f32x4 a, f32x4 b) { u32x4 w; w.x = cvt_pk_bf16(a[0], a[1]); w.y = cvt_pk_bf16(a[2], a[3]); w.z = cvt_pk_bf16(b[0], b[1]); w.w = cvt_pk_bf16(b[2], b[3]); return w; }
; #define EPI_END } asm volatile("" ::: "memory"); }
;     __device__ __forceinline__ void operator()(const f32x4 (&acc)[2][2][4][2], const pg8::Unit& u, int wr, int wc, int fr, int fq) const {
;     ...
;             EPI_BEGIN { v0 += *(const f32x4*)(bias + col); v1 += *(const f32x4*)(bias + col + 4);
;                 if (col < 2048) { *(u32x4*)(o0 + (size_t)row * 2048 + col) = pack8(v0 * qs, v1 * qs); }
;                 else if (col < 2304) { *(u32x4*)(o1 + (size_t)row * 256 + (col - 2048)) = pack8(v0, v1); }
;                 else { const int d = col - 2304, b = row >> 13, t = row & 8191; bf16_t* vp = o2 + ((size_t)(b * 256 + d)) * 8192 + t; const u32x4 w = pack8(v0, v1);
;                     vp[0] = (bf16_t)(w.x & 0xffff); vp[8192] = (bf16_t)(w.x >> 16); vp[2 * 8192] = (bf16_t)(w.y & 0xffff); vp[3 * 8192] = (bf16_t)(w.y >> 16);
;                     vp[4 * 8192] = (bf16_t)(w.z & 0xffff); vp[5 * 8192] = (bf16_t)(w.z >> 16); vp[6 * 8192] = (bf16_t)(w.w & 0xffff); vp[7 * 8192] = (bf16_t)(w.w >> 16); } } EPI_END
.LBB0_959:
	s_or_b64 exec, exec, s[18:19]
	s_nop 1
	v_mov_b32_e32 v128, v198
	v_mov_b32_e32 v129, v199
	v_mov_b32_e32 v130, v200
	v_mov_b32_e32 v131, v201
	v_mov_b32_e32 v168, v202
	v_mov_b32_e32 v169, v203
	v_mov_b32_e32 v170, v204
	v_mov_b32_e32 v171, v205
	v_pk_add_f32 v[162:163], v[38:39], v[130:131]
	v_pk_add_f32 v[128:129], v[36:37], v[128:129]
	v_pk_add_f32 v[160:161], v[34:35], v[170:171]
	v_pk_add_f32 v[130:131], v[32:33], v[168:169]
	s_and_saveexec_b64 s[18:19], s[46:47]
	s_xor_b64 s[18:19], exec, s[18:19]
	s_cbranch_execz .LBB0_964
	s_cmpk_lt_u32 s41, 0x900
	s_mov_b64 s[20:21], -1
	s_cbranch_scc1 .LBB0_962
	v_add_u32_e32 v132, v159, v155
	v_ashrrev_i32_e32 v133, 31, v132
	v_lshlrev_b64 v[132:133], 14, v[132:133]
	v_lshl_add_u64 v[132:133], s[70:71], 0, v[132:133]
	v_lshlrev_b32_e32 v180, 1, v166
	v_lshl_add_u64 v[132:133], v[132:133], 0, v[180:181]
	v_add_co_u32_e32 v164, vcc, s1, v132
	v_cvt_pk_bf16_f32 v166, v128, v129
	v_cvt_pk_bf16_f32 v167, v162, v163
	v_cvt_pk_bf16_f32 v168, v130, v131
	v_cvt_pk_bf16_f32 v169, v160, v161
	s_nop 1
	v_addc_co_u32_e32 v165, vcc, 0, v133, vcc
	global_store_short_d16_hi v[164:165], v166, off
	v_add_co_u32_e32 v164, vcc, s96, v132
	s_mov_b32 s20, 0xc000
	s_nop 0
	v_addc_co_u32_e32 v165, vcc, 0, v133, vcc
	global_store_short v[164:165], v167, off
	v_add_co_u32_e32 v164, vcc, s20, v132
	s_mov_b32 s20, 0x10000
	s_nop 0
	v_addc_co_u32_e32 v165, vcc, 0, v133, vcc
	global_store_short_d16_hi v[164:165], v167, off
	v_add_co_u32_e32 v164, vcc, s20, v132
	global_store_short v[132:133], v166, off
	s_nop 0
	v_addc_co_u32_e32 v165, vcc, 0, v133, vcc
	global_store_short v[164:165], v168, off
	v_add_co_u32_e32 v164, vcc, 0x14000, v132
	s_mov_b64 s[20:21], 0
	s_nop 0
	v_addc_co_u32_e32 v165, vcc, 0, v133, vcc
	global_store_short_d16_hi v[164:165], v168, off
	v_add_co_u32_e32 v164, vcc, 0x18000, v132
	s_nop 1
	v_addc_co_u32_e32 v165, vcc, 0, v133, vcc
	v_add_co_u32_e32 v132, vcc, 0x1c000, v132
	global_store_short v[164:165], v169, off
	s_nop 0
	v_addc_co_u32_e32 v133, vcc, 0, v133, vcc
	global_store_short_d16_hi v[132:133], v169, off

; __device__ __forceinline__ u32x4 pack8(f32x4 a, f32x4 b) { u32x4 w; w.x = cvt_pk_bf16(a[0], a[1]); w.y = cvt_pk_bf16(a[2], a[3]); w.z = cvt_pk_bf16(b[0], b[1]); w.w = cvt_pk_bf16(b[2], b[3]); return w; }
; #define EPI_END } asm volatile("" ::: "memory"); }
;     __device__ __forceinline__ void operator()(const f32x4 (&acc)[2][2][4][2], const pg8::Unit& u, int wr, int wc, int fr, int fq) const {
;     ...
;             EPI_BEGIN { v0 += *(const f32x4*)(bias + col); v1 += *(const f32x4*)(bias + col + 4);
;                 if (col < 2048) { *(u32x4*)(o0 + (size_t)row * 2048 + col) = pack8(v0 * qs, v1 * qs); }
;                 else if (col < 2304) { *(u32x4*)(o1 + (size_t)row * 256 + (col - 2048)) = pack8(v0, v1); }
;                 else { const int d = col - 2304, b = row >> 13, t = row & 8191; bf16_t* vp = o2 + ((size_t)(b * 256 + d)) * 8192 + t; const u32x4 w = pack8(v0, v1);
;                     vp[0] = (bf16_t)(w.x & 0xffff); vp[8192] = (bf16_t)(w.x >> 16); vp[2 * 8192] = (bf16_t)(w.y & 0xffff); vp[3 * 8192] = (bf16_t)(w.y >> 16);
;                     vp[4 * 8192] = (bf16_t)(w.z & 0xffff); vp[5 * 8192] = (bf16_t)(w.z >> 16); vp[6 * 8192] = (bf16_t)(w.w & 0xffff); vp[7 * 8192] = (bf16_t)(w.w >> 16); } } EPI_END
.LBB0_966:
	s_or_b64 exec, exec, s[18:19]
	v_add_u32_e32 v160, 0xa0, v158
	v_ashrrev_i32_e32 v161, 31, v160
	v_and_b32_e32 v166, 0x1fef, v160
	v_lshlrev_b64 v[136:137], 9, v[160:161]
	s_nop 1
	v_mov_b32_e32 v128, v190
	v_mov_b32_e32 v129, v191
	v_mov_b32_e32 v130, v192
	v_mov_b32_e32 v131, v193
	v_mov_b32_e32 v168, v194
	v_mov_b32_e32 v169, v195
	v_mov_b32_e32 v170, v196
	v_mov_b32_e32 v171, v197
	v_pk_add_f32 v[164:165], v[30:31], v[130:131]
	v_pk_add_f32 v[128:129], v[28:29], v[128:129]
	v_pk_add_f32 v[162:163], v[26:27], v[170:171]
	v_pk_add_f32 v[130:131], v[24:25], v[168:169]
	s_and_saveexec_b64 s[18:19], s[44:45]
	s_xor_b64 s[18:19], exec, s[18:19]
	s_cbranch_execz .LBB0_971
	s_cmpk_lt_u32 s41, 0x900
	s_mov_b64 s[20:21], -1
	s_cbranch_scc1 .LBB0_969
	v_add_u32_e32 v132, v159, v156
	v_ashrrev_i32_e32 v133, 31, v132
	v_lshlrev_b64 v[132:133], 14, v[132:133]
	v_lshl_add_u64 v[132:133], s[70:71], 0, v[132:133]
	v_lshlrev_b32_e32 v180, 1, v166
	v_lshl_add_u64 v[132:133], v[132:133], 0, v[180:181]
	v_add_co_u32_e32 v168, vcc, s1, v132
	v_cvt_pk_bf16_f32 v167, v128, v129
	v_cvt_pk_bf16_f32 v170, v164, v165
	v_cvt_pk_bf16_f32 v171, v130, v131
	v_cvt_pk_bf16_f32 v172, v162, v163
	s_nop 1
	v_addc_co_u32_e32 v169, vcc, 0, v133, vcc
	global_store_short_d16_hi v[168:169], v167, off
	v_add_co_u32_e32 v168, vcc, s96, v132
	s_mov_b32 s20, 0xc000
	s_nop 0
	v_addc_co_u32_e32 v169, vcc, 0, v133, vcc
	global_store_short v[168:169], v170, off
	v_add_co_u32_e32 v168, vcc, s20, v132
	s_mov_b32 s20, 0x10000
	s_nop 0
	v_addc_co_u32_e32 v169, vcc, 0, v133, vcc
	global_store_short_d16_hi v[168:169], v170, off
	v_add_co_u32_e32 v168, vcc, s20, v132
	global_store_short v[132:133], v167, off
	s_nop 0
	v_addc_co_u32_e32 v169, vcc, 0, v133, vcc
	global_store_short v[168:169], v171, off
	v_add_co_u32_e32 v168, vcc, 0x14000, v132
	s_mov_b64 s[20:21], 0
	s_nop 0
	v_addc_co_u32_e32 v169, vcc, 0, v133, vcc
	global_store_short_d16_hi v[168:169], v171, off
	v_add_co_u32_e32 v168, vcc, 0x18000, v132
	s_nop 1
	v_addc_co_u32_e32 v169, vcc, 0, v133, vcc
	v_add_co_u32_e32 v132, vcc, 0x1c000, v132
	global_store_short v[168:169], v172, off
	s_nop 0
	v_addc_co_u32_e32 v133, vcc, 0, v133, vcc
	global_store_short_d16_hi v[132:133], v172, off

; __device__ __forceinline__ u32x4 pack8(f32x4 a, f32x4 b) { u32x4 w; w.x = cvt_pk_bf16(a[0], a[1]); w.y = cvt_pk_bf16(a[2], a[3]); w.z = cvt_pk_bf16(b[0], b[1]); w.w = cvt_pk_bf16(b[2], b[3]); return w; }
; #define EPI_END } asm volatile("" ::: "memory"); }
;     __device__ __forceinline__ void operator()(const f32x4 (&acc)[2][2][4][2], const pg8::Unit& u, int wr, int wc, int fr, int fq) const {
;     ...
;             EPI_BEGIN { v0 += *(const f32x4*)(bias + col); v1 += *(const f32x4*)(bias + col + 4);
;                 if (col < 2048) { *(u32x4*)(o0 + (size_t)row * 2048 + col) = pack8(v0 * qs, v1 * qs); }
;                 else if (col < 2304) { *(u32x4*)(o1 + (size_t)row * 256 + (col - 2048)) = pack8(v0, v1); }
;                 else { const int d = col - 2304, b = row >> 13, t = row & 8191; bf16_t* vp = o2 + ((size_t)(b * 256 + d)) * 8192 + t; const u32x4 w = pack8(v0, v1);
;                     vp[0] = (bf16_t)(w.x & 0xffff); vp[8192] = (bf16_t)(w.x >> 16); vp[2 * 8192] = (bf16_t)(w.y & 0xffff); vp[3 * 8192] = (bf16_t)(w.y >> 16);
;                     vp[4 * 8192] = (bf16_t)(w.z & 0xffff); vp[5 * 8192] = (bf16_t)(w.z >> 16); vp[6 * 8192] = (bf16_t)(w.w & 0xffff); vp[7 * 8192] = (bf16_t)(w.w >> 16); } } EPI_END
.LBB0_973:
	s_or_b64 exec, exec, s[18:19]
	s_nop 1
	v_mov_b32_e32 v128, v198
	v_mov_b32_e32 v129, v199
	v_mov_b32_e32 v130, v200
	v_mov_b32_e32 v131, v201
	v_mov_b32_e32 v168, v202
	v_mov_b32_e32 v169, v203
	v_mov_b32_e32 v170, v204
	v_mov_b32_e32 v171, v205
	v_pk_add_f32 v[162:163], v[22:23], v[130:131]
	v_pk_add_f32 v[128:129], v[20:21], v[128:129]
	v_pk_add_f32 v[160:161], v[18:19], v[170:171]
	v_pk_add_f32 v[130:131], v[16:17], v[168:169]
	s_and_saveexec_b64 s[18:19], s[46:47]
	s_xor_b64 s[18:19], exec, s[18:19]
	s_cbranch_execz .LBB0_978
	s_cmpk_lt_u32 s41, 0x900
	s_mov_b64 s[20:21], -1
	s_cbranch_scc1 .LBB0_976
	v_add_u32_e32 v132, v159, v155
	v_ashrrev_i32_e32 v133, 31, v132
	v_lshlrev_b64 v[132:133], 14, v[132:133]
	v_lshl_add_u64 v[132:133], s[70:71], 0, v[132:133]
	v_lshlrev_b32_e32 v180, 1, v166
	v_lshl_add_u64 v[132:133], v[132:133], 0, v[180:181]
	v_add_co_u32_e32 v164, vcc, s1, v132
	v_cvt_pk_bf16_f32 v166, v128, v129
	v_cvt_pk_bf16_f32 v167, v162, v163
	v_cvt_pk_bf16_f32 v168, v130, v131
	v_cvt_pk_bf16_f32 v169, v160, v161
	s_nop 1
	v_addc_co_u32_e32 v165, vcc, 0, v133, vcc
	global_store_short_d16_hi v[164:165], v166, off
	v_add_co_u32_e32 v164, vcc, s96, v132
	s_mov_b32 s20, 0xc000
	s_nop 0
	v_addc_co_u32_e32 v165, vcc, 0, v133, vcc
	global_store_short v[164:165], v167, off
	v_add_co_u32_e32 v164, vcc, s20, v132
	s_mov_b32 s20, 0x10000
	s_nop 0
	v_addc_co_u32_e32 v165, vcc, 0, v133, vcc
	global_store_short_d16_hi v[164:165], v167, off
	v_add_co_u32_e32 v164, vcc, s20, v132
	global_store_short v[132:133], v166, off
	s_nop 0
	v_addc_co_u32_e32 v165, vcc, 0, v133, vcc
	global_store_short v[164:165], v168, off
	v_add_co_u32_e32 v164, vcc, 0x14000, v132
	s_mov_b64 s[20:21], 0
	s_nop 0
	v_addc_co_u32_e32 v165, vcc, 0, v133, vcc
	global_store_short_d16_hi v[164:165], v168, off
	v_add_co_u32_e32 v164, vcc, 0x18000, v132
	s_nop 1
	v_addc_co_u32_e32 v165, vcc, 0, v133, vcc
	v_add_co_u32_e32 v132, vcc, 0x1c000, v132
	global_store_short v[164:165], v169, off
	s_nop 0
	v_addc_co_u32_e32 v133, vcc, 0, v133, vcc
	global_store_short_d16_hi v[132:133], v169, off

; __device__ __forceinline__ u32x4 pack8(f32x4 a, f32x4 b) { u32x4 w; w.x = cvt_pk_bf16(a[0], a[1]); w.y = cvt_pk_bf16(a[2], a[3]); w.z = cvt_pk_bf16(b[0], b[1]); w.w = cvt_pk_bf16(b[2], b[3]); return w; }
; #define EPI_END } asm volatile("" ::: "memory"); }
;     __device__ __forceinline__ void operator()(const f32x4 (&acc)[2][2][4][2], const pg8::Unit& u, int wr, int wc, int fr, int fq) const {
;     ...
;             EPI_BEGIN { v0 += *(const f32x4*)(bias + col); v1 += *(const f32x4*)(bias + col + 4);
;                 if (col < 2048) { *(u32x4*)(o0 + (size_t)row * 2048 + col) = pack8(v0 * qs, v1 * qs); }
;                 else if (col < 2304) { *(u32x4*)(o1 + (size_t)row * 256 + (col - 2048)) = pack8(v0, v1); }
;                 else { const int d = col - 2304, b = row >> 13, t = row & 8191; bf16_t* vp = o2 + ((size_t)(b * 256 + d)) * 8192 + t; const u32x4 w = pack8(v0, v1);
;                     vp[0] = (bf16_t)(w.x & 0xffff); vp[8192] = (bf16_t)(w.x >> 16); vp[2 * 8192] = (bf16_t)(w.y & 0xffff); vp[3 * 8192] = (bf16_t)(w.y >> 16);
;                     vp[4 * 8192] = (bf16_t)(w.z & 0xffff); vp[5 * 8192] = (bf16_t)(w.z >> 16); vp[6 * 8192] = (bf16_t)(w.w & 0xffff); vp[7 * 8192] = (bf16_t)(w.w >> 16); } } EPI_END
.LBB0_980:
	s_or_b64 exec, exec, s[18:19]
	v_add_u32_e32 v160, 0xb0, v158
	v_ashrrev_i32_e32 v161, 31, v160
	v_and_b32_e32 v166, 0x1fff, v160
	v_lshlrev_b64 v[136:137], 9, v[160:161]
	s_nop 1
	v_mov_b32_e32 v128, v190
	v_mov_b32_e32 v129, v191
	v_mov_b32_e32 v130, v192
	v_mov_b32_e32 v131, v193
	v_mov_b32_e32 v168, v194
	v_mov_b32_e32 v169, v195
	v_mov_b32_e32 v170, v196
	v_mov_b32_e32 v171, v197
	v_pk_add_f32 v[164:165], v[14:15], v[130:131]
	v_pk_add_f32 v[128:129], v[12:13], v[128:129]
	v_pk_add_f32 v[162:163], v[10:11], v[170:171]
	v_pk_add_f32 v[130:131], v[8:9], v[168:169]
	s_and_saveexec_b64 s[18:19], s[44:45]
	s_xor_b64 s[18:19], exec, s[18:19]
	s_cbranch_execz .LBB0_985
	s_cmpk_lt_u32 s41, 0x900
	s_mov_b64 s[20:21], -1
	s_cbranch_scc1 .LBB0_983
	v_add_u32_e32 v132, v159, v156
	v_ashrrev_i32_e32 v133, 31, v132
	v_lshlrev_b64 v[132:133], 14, v[132:133]
	v_lshl_add_u64 v[132:133], s[70:71], 0, v[132:133]
	v_lshlrev_b32_e32 v180, 1, v166
	v_lshl_add_u64 v[132:133], v[132:133], 0, v[180:181]
	v_add_co_u32_e32 v168, vcc, s1, v132
	v_cvt_pk_bf16_f32 v167, v128, v129
	v_cvt_pk_bf16_f32 v170, v164, v165
	v_cvt_pk_bf16_f32 v171, v130, v131
	v_cvt_pk_bf16_f32 v172, v162, v163
	s_nop 1
	v_addc_co_u32_e32 v169, vcc, 0, v133, vcc
	global_store_short_d16_hi v[168:169], v167, off
	v_add_co_u32_e32 v168, vcc, s96, v132
	s_mov_b32 s20, 0xc000
	s_nop 0
	v_addc_co_u32_e32 v169, vcc, 0, v133, vcc
	global_store_short v[168:169], v170, off
	v_add_co_u32_e32 v168, vcc, s20, v132
	s_mov_b32 s20, 0x10000
	s_nop 0
	v_addc_co_u32_e32 v169, vcc, 0, v133, vcc
	global_store_short_d16_hi v[168:169], v170, off
	v_add_co_u32_e32 v168, vcc, s20, v132
	global_store_short v[132:133], v167, off
	s_nop 0
	v_addc_co_u32_e32 v169, vcc, 0, v133, vcc
	global_store_short v[168:169], v171, off
	v_add_co_u32_e32 v168, vcc, 0x14000, v132
	s_mov_b64 s[20:21], 0
	s_nop 0
	v_addc_co_u32_e32 v169, vcc, 0, v133, vcc
	global_store_short_d16_hi v[168:169], v171, off
	v_add_co_u32_e32 v168, vcc, 0x18000, v132
	s_nop 1
	v_addc_co_u32_e32 v169, vcc, 0, v133, vcc
	v_add_co_u32_e32 v132, vcc, 0x1c000, v132
	global_store_short v[168:169], v172, off
	s_nop 0
	v_addc_co_u32_e32 v133, vcc, 0, v133, vcc
	global_store_short_d16_hi v[132:133], v172, off

; __device__ __forceinline__ u32x4 pack8(f32x4 a, f32x4 b) { u32x4 w; w.x = cvt_pk_bf16(a[0], a[1]); w.y = cvt_pk_bf16(a[2], a[3]); w.z = cvt_pk_bf16(b[0], b[1]); w.w = cvt_pk_bf16(b[2], b[3]); return w; }
; #define EPI_END } asm volatile("" ::: "memory"); }
;     __device__ __forceinline__ void operator()(const f32x4 (&acc)[2][2][4][2], const pg8::Unit& u, int wr, int wc, int fr, int fq) const {
;     ...
;             EPI_BEGIN { v0 += *(const f32x4*)(bias + col); v1 += *(const f32x4*)(bias + col + 4);
;                 if (col < 2048) { *(u32x4*)(o0 + (size_t)row * 2048 + col) = pack8(v0 * qs, v1 * qs); }
;                 else if (col < 2304) { *(u32x4*)(o1 + (size_t)row * 256 + (col - 2048)) = pack8(v0, v1); }
;                 else { const int d = col - 2304, b = row >> 13, t = row & 8191; bf16_t* vp = o2 + ((size_t)(b * 256 + d)) * 8192 + t; const u32x4 w = pack8(v0, v1);
;                     vp[0] = (bf16_t)(w.x & 0xffff); vp[8192] = (bf16_t)(w.x >> 16); vp[2 * 8192] = (bf16_t)(w.y & 0xffff); vp[3 * 8192] = (bf16_t)(w.y >> 16);
;                     vp[4 * 8192] = (bf16_t)(w.z & 0xffff); vp[5 * 8192] = (bf16_t)(w.z >> 16); vp[6 * 8192] = (bf16_t)(w.w & 0xffff); vp[7 * 8192] = (bf16_t)(w.w >> 16); } } EPI_END
.LBB0_987:
	s_or_b64 exec, exec, s[18:19]
	s_nop 1
	v_mov_b32_e32 v128, v198
	v_mov_b32_e32 v129, v199
	v_mov_b32_e32 v130, v200
	v_mov_b32_e32 v131, v201
	v_mov_b32_e32 v162, v202
	v_mov_b32_e32 v163, v203
	v_mov_b32_e32 v164, v204
	v_mov_b32_e32 v165, v205
	v_pk_add_f32 v[160:161], v[6:7], v[130:131]
	v_pk_add_f32 v[128:129], v[4:5], v[128:129]
	v_pk_add_f32 v[134:135], v[2:3], v[164:165]
	v_pk_add_f32 v[130:131], v[0:1], v[162:163]
	s_and_saveexec_b64 s[18:19], s[46:47]
	s_xor_b64 s[18:19], exec, s[18:19]
	s_cbranch_execz .LBB0_992
	s_cmpk_lt_u32 s41, 0x900
	s_mov_b64 s[20:21], -1
	s_cbranch_scc1 .LBB0_990
	v_add_u32_e32 v132, v159, v155
	v_ashrrev_i32_e32 v133, 31, v132
	v_lshlrev_b64 v[132:133], 14, v[132:133]
	v_lshl_add_u64 v[132:133], s[70:71], 0, v[132:133]
	v_lshlrev_b32_e32 v180, 1, v166
	v_lshl_add_u64 v[132:133], v[132:133], 0, v[180:181]
	v_add_co_u32_e32 v162, vcc, s1, v132
	v_cvt_pk_bf16_f32 v155, v128, v129
	v_cvt_pk_bf16_f32 v157, v160, v161
	v_cvt_pk_bf16_f32 v159, v130, v131
	v_cvt_pk_bf16_f32 v164, v134, v135
	s_nop 1
	v_addc_co_u32_e32 v163, vcc, 0, v133, vcc
	global_store_short_d16_hi v[162:163], v155, off
	v_add_co_u32_e32 v162, vcc, s96, v132
	s_mov_b32 s20, 0xc000
	s_nop 0
	v_addc_co_u32_e32 v163, vcc, 0, v133, vcc
	global_store_short v[162:163], v157, off
	v_add_co_u32_e32 v162, vcc, s20, v132
	s_mov_b32 s20, 0x10000
	s_nop 0
	v_addc_co_u32_e32 v163, vcc, 0, v133, vcc
	global_store_short_d16_hi v[162:163], v157, off
	v_add_co_u32_e32 v162, vcc, s20, v132
	global_store_short v[132:133], v155, off
	s_nop 0
	v_addc_co_u32_e32 v163, vcc, 0, v133, vcc
	global_store_short v[162:163], v159, off
	v_add_co_u32_e32 v162, vcc, 0x14000, v132
	s_mov_b64 s[20:21], 0
	s_nop 0
	v_addc_co_u32_e32 v163, vcc, 0, v133, vcc
	global_store_short_d16_hi v[162:163], v159, off
	v_add_co_u32_e32 v162, vcc, 0x18000, v132
	s_nop 1
	v_addc_co_u32_e32 v163, vcc, 0, v133, vcc
	v_add_co_u32_e32 v132, vcc, 0x1c000, v132
	global_store_short v[162:163], v164, off
	s_nop 0
	v_addc_co_u32_e32 v133, vcc, 0, v133, vcc
	global_store_short_d16_hi v[132:133], v164, off
